# split grid barrier after mLSTM: arrive in place, wait only before the next GEMM's first tile epilogue (GEMM reads nothing mLSTM wrote)
# speedup vs baseline: 1.0091x; 1.0031x over previous
; __device__ __forceinline__ void xcd_barrier(const XcdBarrier& b) {
;     asm volatile("s_waitcnt vmcnt(0)" ::: "memory");
;     __syncthreads();
;     if (threadIdx.x == 0) {
;     __device__ bool next(int i, Unit& u) const {
;         const long L = (long)i * G + c; if (L >= nwg) return false;
;         int wgid = (int)L; { const int q = nwg / NXCD, r = nwg % NXCD, xcd = wgid % NXCD, off = wgid / NXCD; wgid = (xcd < r ? xcd * (q + 1) : r * (q + 1) + (xcd - r) * q) + off; }
;         const int nig = WGM * nN, gid = wgid / nig, fm = gid * WGM, gsz = (nM - fm) < WGM ? (nM - fm) : WGM;
;         u.pm = fm + ((wgid % nig) % gsz); u.pn = (wgid % nig) / gsz; return true;
.LBB0_359:
	s_mov_b32 s99, 0
	s_mov_b32 s100, 0
	s_cmp_gt_i32 s91, 4
	v_readlane_b32 s2, v254, 25
	s_cselect_b64 s[0:1], -1, 0
	v_readlane_b32 s3, v254, 26
	s_and_b64 s[2:3], s[2:3], s[0:1]
	s_andn2_b64 vcc, exec, s[2:3]
	s_cbranch_vccnz .LBB0_409
	s_cmp_eq_u32 s82, 0x100
	s_cselect_b32 s99, 1, 0
	s_mov_b32 s100, 1
	s_cmpk_lt_i32 s84, 0x700
	s_cselect_b64 s[2:3], -1, 0
	s_cmpk_gt_i32 s84, 0x6ff
	v_readfirstlane_b32 s33, v212
	s_cbranch_scc1 .Lp4e_412
	s_ashr_i32 s4, s84, 31
	s_lshr_b32 s4, s4, 29
	s_add_i32 s4, s84, s4
	s_ashr_i32 s5, s4, 3
	s_and_b32 s4, s4, -8
	s_sub_i32 s4, s84, s4
	s_cmp_lt_i32 s4, 0
	s_movk_i32 s6, 0xe1
	s_cselect_b32 s6, s6, 0xe0
	s_mul_i32 s4, s4, s6
	s_add_i32 s4, s4, s5
	s_mul_hi_i32 s5, s4, 0x92492493
	s_add_i32 s5, s5, s4
	s_lshr_b32 s6, s5, 31
	s_ashr_i32 s5, s5, 6
	s_add_i32 s5, s5, s6
	s_lshl_b32 s6, s5, 2
	s_mulk_i32 s5, 0x70
	s_sub_i32 s4, s4, s5
	s_bfe_i32 s5, s4, 0x80000
	s_bfe_u32 s5, s5, 0x2000d
	s_add_i32 s5, s4, s5
	s_bfe_i32 s7, s5, 0x80000
	s_and_b32 s5, s5, 0xfc
	s_sub_i32 s4, s4, s5
	s_sext_i32_i16 s7, s7
	s_sext_i32_i8 s4, s4
	s_add_i32 s6, s6, s4
	s_ashr_i32 s4, s7, 2

; __device__ __forceinline__ unsigned xb_ld(unsigned* p)              { return __hip_atomic_load(p, __ATOMIC_RELAXED, __HIP_MEMORY_SCOPE_AGENT); }
; __device__ __forceinline__ unsigned xb_add(unsigned* p, unsigned v) { return __hip_atomic_fetch_add(p, v, __ATOMIC_RELAXED, __HIP_MEMORY_SCOPE_AGENT); }
; #define XB_SPIN(cond, bar) do { unsigned _sp = 0; while (cond) { __builtin_amdgcn_s_sleep(1); \
;     if ((++_sp & 255u) == 0u) { if (xb_ld(&(bar)[XB_TMO])) break; if (_sp > XB_SPIN_CAP) { atomicAdd(&(bar)[XB_TMO], 1u); break; } } } } while (0)
; __device__ __forceinline__ void xcd_barrier(const XcdBarrier& b) {
;     ...
;         const unsigned old = xb_add(&bar[XB_XSUB(b.x)], 1u);
;         const unsigned gen = old / nloc;
;         if (old + 1u == (gen + 1u) * nloc) {
;             __builtin_amdgcn_fence(__ATOMIC_RELEASE, "agent");
;             asm volatile("s_waitcnt vmcnt(0)" ::: "memory");
;             const unsigned og = xb_add(&bar[XB_TOP], 1u);
;             const unsigned tg = og / nx;
;             if (og + 1u == (tg + 1u) * nx) xb_add(&bar[XB_TOPGEN], 1u);
;             else XB_SPIN(xb_ld(&bar[XB_TOPGEN]) == tg, bar);
;             __builtin_amdgcn_fence(__ATOMIC_ACQUIRE, "agent");
;             xb_add(&bar[XB_XGEN(b.x)], 1u);
;             asm volatile("s_waitcnt vmcnt(0)" ::: "memory");
;         } else {
;             XB_SPIN(xb_ld(&bar[XB_XGEN(b.x)]) == gen, bar);
.LBB0_376:
	v_readlane_b32 s4, v254, 3
	s_lshl_b32 s4, s4, 8
	s_add_u32 s4, s92, s4
	s_addc_u32 s5, s93, 0
	v_mov_b32_e32 v1, 0x1000
	v_mov_b32_e32 v3, 1
	global_atomic_add v3, v1, v3, s[4:5] offset:1024 sc0
	v_cvt_f32_u32_e32 v1, v2
	v_sub_u32_e32 v4, 0, v2
	v_rcp_iflag_f32_e32 v1, v1
	s_nop 0
	v_mul_f32_e32 v1, 0x4f7ffffe, v1
	v_cvt_u32_f32_e32 v1, v1
	v_mul_lo_u32 v4, v4, v1
	v_mul_hi_u32 v4, v1, v4
	v_add_u32_e32 v1, v1, v4
	s_waitcnt vmcnt(0)
	v_mul_hi_u32 v1, v3, v1
	v_mul_lo_u32 v4, v1, v2
	v_sub_u32_e32 v4, v3, v4
	v_add_u32_e32 v5, 1, v1
	v_cmp_ge_u32_e32 vcc, v4, v2
	v_add_u32_e32 v3, 1, v3
	s_nop 0
	v_cndmask_b32_e32 v1, v1, v5, vcc
	v_sub_u32_e32 v5, v4, v2
	v_cndmask_b32_e32 v4, v4, v5, vcc
	v_add_u32_e32 v5, 1, v1
	v_cmp_ge_u32_e32 vcc, v4, v2
	s_nop 1
	v_cndmask_b32_e32 v1, v1, v5, vcc
	v_mul_lo_u32 v4, v2, v1
	v_add_u32_e32 v2, v4, v2
	v_cmp_ne_u32_e32 vcc, v3, v2
	s_and_saveexec_b64 s[6:7], vcc
	s_xor_b64 s[6:7], exec, s[6:7]
	s_cbranch_execz .LBB0_390
	s_cmp_eq_u32 s99, 1
	s_cbranch_scc1 .Lsk3_nl
	s_waitcnt lgkmcnt(0)
	v_mov_b32_e32 v0, 0x2000
	global_load_dword v0, v0, s[4:5] offset:1024 sc1
	s_add_u32 s12, s4, 0x2400
	s_addc_u32 s13, s5, 0
	s_waitcnt vmcnt(0)
	v_cmp_eq_u32_e32 vcc, v0, v1
	s_and_saveexec_b64 s[8:9], vcc
	s_cbranch_execz .LBB0_389
	s_add_u32 s10, s88, 0xffc0200
	s_addc_u32 s11, s89, 0
	s_mov_b32 s24, 1
	s_mov_b64 s[14:15], 0
	v_mov_b32_e32 v0, 0
	s_branch .LBB0_380

; __device__ __forceinline__ unsigned xb_ld(unsigned* p)              { return __hip_atomic_load(p, __ATOMIC_RELAXED, __HIP_MEMORY_SCOPE_AGENT); }
; #define XB_SPIN(cond, bar) do { unsigned _sp = 0; while (cond) { __builtin_amdgcn_s_sleep(1); \
;     if ((++_sp & 255u) == 0u) { if (xb_ld(&(bar)[XB_TMO])) break; if (_sp > XB_SPIN_CAP) { atomicAdd(&(bar)[XB_TMO], 1u); break; } } } } while (0)
; __device__ __forceinline__ void xcd_barrier(const XcdBarrier& b) {
;     ...
;             XB_SPIN(xb_ld(&bar[XB_XGEN(b.x)]) == gen, bar);
;             __builtin_amdgcn_fence(__ATOMIC_ACQUIRE, "agent");
;             asm volatile("s_waitcnt vmcnt(0)" ::: "memory");
.Lsk3_nl:
	s_waitcnt vmcnt(0)
	buffer_inv sc1
	s_waitcnt vmcnt(0)

; __device__ __forceinline__ unsigned xb_ld(unsigned* p)              { return __hip_atomic_load(p, __ATOMIC_RELAXED, __HIP_MEMORY_SCOPE_AGENT); }
; __device__ __forceinline__ unsigned xb_add(unsigned* p, unsigned v) { return __hip_atomic_fetch_add(p, v, __ATOMIC_RELAXED, __HIP_MEMORY_SCOPE_AGENT); }
; #define XB_SPIN(cond, bar) do { unsigned _sp = 0; while (cond) { __builtin_amdgcn_s_sleep(1); \
;     if ((++_sp & 255u) == 0u) { if (xb_ld(&(bar)[XB_TMO])) break; if (_sp > XB_SPIN_CAP) { atomicAdd(&(bar)[XB_TMO], 1u); break; } } } } while (0)
; __device__ __forceinline__ void xcd_barrier(const XcdBarrier& b) {
;     ...
;         const unsigned old = xb_add(&bar[XB_XSUB(b.x)], 1u);
;         const unsigned gen = old / nloc;
;         if (old + 1u == (gen + 1u) * nloc) {
;             __builtin_amdgcn_fence(__ATOMIC_RELEASE, "agent");
;             asm volatile("s_waitcnt vmcnt(0)" ::: "memory");
;             const unsigned og = xb_add(&bar[XB_TOP], 1u);
;             const unsigned tg = og / nx;
;             if (og + 1u == (tg + 1u) * nx) xb_add(&bar[XB_TOPGEN], 1u);
;             else XB_SPIN(xb_ld(&bar[XB_TOPGEN]) == tg, bar);
.LBB0_393:
	s_or_b64 exec, exec, s[8:9]
	v_cvt_f32_u32_e32 v3, v0
	s_waitcnt vmcnt(0)
	v_readfirstlane_b32 s6, v2
	s_add_u32 s8, s88, 0xffc3500
	s_addc_u32 s9, s89, 0
	v_rcp_iflag_f32_e32 v3, v3
	v_add_u32_e32 v1, s6, v1
	v_add_u32_e32 v4, 1, v1
	s_mov_b64 s[10:11], -1
	v_mul_f32_e32 v2, 0x4f7ffffe, v3
	v_cvt_u32_f32_e32 v2, v2
	v_sub_u32_e32 v3, 0, v0
	v_mul_lo_u32 v3, v3, v2
	v_mul_hi_u32 v3, v2, v3
	v_add_u32_e32 v2, v2, v3
	v_mul_hi_u32 v2, v1, v2
	v_mul_lo_u32 v3, v2, v0
	v_sub_u32_e32 v1, v1, v3
	v_add_u32_e32 v5, 1, v2
	v_cmp_ge_u32_e32 vcc, v1, v0
	v_sub_u32_e32 v3, v1, v0
	s_nop 0
	v_cndmask_b32_e32 v2, v2, v5, vcc
	v_cndmask_b32_e32 v1, v1, v3, vcc
	v_add_u32_e32 v3, 1, v2
	v_cmp_ge_u32_e32 vcc, v1, v0
	s_nop 1
	v_cndmask_b32_e32 v2, v2, v3, vcc
	v_mul_lo_u32 v1, v0, v2
	v_add_u32_e32 v0, v1, v0
	v_cmp_ne_u32_e32 vcc, v4, v0
	v_mov_b64_e32 v[0:1], s[8:9]
	s_and_saveexec_b64 s[6:7], vcc
	s_cbranch_execz .LBB0_405
	s_cmp_eq_u32 s99, 1
	s_cbranch_scc0 .Lsk3_ld_no
	s_mov_b64 s[14:15], 0
	s_branch .Lsk3_ld
.Lsk3_ld_no:
	v_mov_b32_e32 v0, 0
	global_load_dword v1, v0, s[8:9] sc1
	s_mov_b64 s[14:15], 0
	s_waitcnt vmcnt(0)
	v_cmp_eq_u32_e32 vcc, v1, v2
	s_and_saveexec_b64 s[12:13], vcc
	s_cbranch_execz .LBB0_404
	s_add_u32 s10, s88, 0xffc0200
	s_addc_u32 s11, s89, 0
	s_mov_b32 s24, 1
	s_branch .LBB0_397

; __device__ __forceinline__ unsigned xb_ld(unsigned* p)              { return __hip_atomic_load(p, __ATOMIC_RELAXED, __HIP_MEMORY_SCOPE_AGENT); }
; __device__ __forceinline__ unsigned xb_add(unsigned* p, unsigned v) { return __hip_atomic_fetch_add(p, v, __ATOMIC_RELAXED, __HIP_MEMORY_SCOPE_AGENT); }
; #define XB_SPIN(cond, bar) do { unsigned _sp = 0; while (cond) { __builtin_amdgcn_s_sleep(1); \
;     if ((++_sp & 255u) == 0u) { if (xb_ld(&(bar)[XB_TMO])) break; if (_sp > XB_SPIN_CAP) { atomicAdd(&(bar)[XB_TMO], 1u); break; } } } } while (0)
; __device__ __forceinline__ void xcd_barrier(const XcdBarrier& b) {
;     ...
;             else XB_SPIN(xb_ld(&bar[XB_TOPGEN]) == tg, bar);
;             __builtin_amdgcn_fence(__ATOMIC_ACQUIRE, "agent");
;             xb_add(&bar[XB_XGEN(b.x)], 1u);
.Lsk3_ld:
	v_mov_b64_e32 v[0:1], s[10:11]
	s_orn2_b64 s[10:11], s[14:15], exec

; #define PG8_STAGE(bufoff, gbase, voff) do { _Pragma("unroll") for (int _i = 0; _i < 2; ++_i) \
;         __builtin_amdgcn_global_load_lds((const unsigned*)((const char*)(gbase) + (voff)[_i]), (LAS unsigned*)(lds + (bufoff) + ldsw + _i * 8192), 16, 0, 0); } while (0)
; #define PG8_LDA(dst, b, h) do { _Pragma("unroll") for (int m = 0; m < 4; ++m) _Pragma("unroll") for (int k = 0; k < 2; ++k) dst[m][k] = *(const LAS bf16x8*)(lds + PG8_SA(b, h) + aoff + m * 2048 + k * 1024); } while (0)
; #define PG8_LDB(dst, b, h) do { _Pragma("unroll") for (int n = 0; n < 2; ++n) _Pragma("unroll") for (int k = 0; k < 2; ++k) dst[n][k] = *(const LAS bf16x8*)(lds + PG8_SB(b, h) + boff + n * 2048 + k * 1024); } while (0)
; #define PG8_MMA(ai, bj, At, Bt) do { __builtin_amdgcn_s_setprio(1); _Pragma("unroll") for (int m = 0; m < 4; ++m) _Pragma("unroll") for (int n = 0; n < 2; ++n) _Pragma("unroll") for (int k = 0; k < 2; ++k) \
;         acc[ai][bj][m][n] = __builtin_amdgcn_mfma_f32_16x16x32_bf16(Bt[n][k], At[m][k], acc[ai][bj][m][n], 0, 0, 0); __builtin_amdgcn_s_setprio(0); } while (0)
; #define PG8_WAIT_V(n) asm volatile("s_waitcnt vmcnt(" #n ")" ::: "memory")
; #define PG8_WAIT_L(n) asm volatile("s_waitcnt lgkmcnt(" #n ")" ::: "memory")
; #define PG8_BAR __builtin_amdgcn_s_barrier()
; #define PG8_SCHED __builtin_amdgcn_sched_barrier(0)
; #define PG8_LDA(dst, b, h) do { _Pragma("unroll") for (int m = 0; m < 4; ++m) _Pragma("unroll") for (int k = 0; k < 2; ++k) dst[m][k] = *(const LAS bf16x8*)(lds + PG8_SA(b, h) + aoff + m * 2048 + k * 1024); } while (0)
; #define PG8_BAR __builtin_amdgcn_s_barrier()
; template <class Epi, bool AFTER = false>
; __device__ __forceinline__ void gemm_phase(LAS unsigned char* lds, const Gemm g, const StaticOrder& S, const Epi& E) {
;     ...
;             PG8_LDB(B0, 0, 0); PG8_SCHED; PG8_LDA(At, 0, 0); PG8_STAGE(PG8_SA(1, 1), a1 + hstep, voffA);
;             PG8_WAIT_L(8); PG8_BAR; PG8_WAIT_L(0); PG8_MMA(0, 0, At, B0); PG8_BAR; PG8_SCHED;
;             PG8_LDB(B1, 0, 1); PG8_STAGE(PG8_SB(0, 0), b2, voffB);
;             PG8_BAR; PG8_WAIT_L(0); PG8_MMA(0, 1, At, B1); PG8_BAR;
;             PG8_LDA(At, 0, 1); PG8_STAGE(PG8_SA(0, 0), a2, voffA);
;             PG8_BAR; PG8_WAIT_L(0); PG8_MMA(1, 0, At, B0); PG8_BAR; PG8_SCHED;
;             PG8_STAGE(PG8_SB(0, 1), b2 + hstep, voffB);
;             PG8_WAIT_V(6); PG8_BAR; PG8_MMA(1, 1, At, B1); PG8_BAR;
.LBB0_420:
	ds_read_b128 v[158:161], v151
	ds_read_b128 v[162:165], v151 offset:1024
	ds_read_b128 v[166:169], v151 offset:2048
	ds_read_b128 v[170:173], v151 offset:3072
	s_add_u32 s24, s22, 0xfffc0080
	s_addc_u32 s25, s23, -1
	s_cmp_eq_u32 s29, 12
	s_cselect_b32 s27, s5, s25
	s_cselect_b32 s26, s7, s24
	s_cselect_b32 s25, s8, s28
	s_cselect_b32 s24, s15, s17
	v_lshl_add_u64 v[148:149], s[22:23], 0, v[140:141]
	s_add_i32 m0, s43, 0xc000
	ds_read_b128 v[174:177], v152
	ds_read_b128 v[178:181], v152 offset:1024
	ds_read_b128 v[182:185], v152 offset:2048
	ds_read_b128 v[186:189], v152 offset:3072
	ds_read_b128 v[192:195], v152 offset:4096
	ds_read_b128 v[196:199], v152 offset:5120
	ds_read_b128 v[200:203], v152 offset:6144
	ds_read_b128 v[204:207], v152 offset:7168
	global_load_lds_dwordx4 v[148:149], off
	v_lshl_add_u64 v[148:149], s[22:23], 0, v[142:143]
	s_add_i32 m0, s43, 0xe000
	s_nop 0
	global_load_lds_dwordx4 v[148:149], off
	s_waitcnt lgkmcnt(8)
	s_barrier
	s_waitcnt lgkmcnt(0)
	s_setprio 1
	s_waitcnt lgkmcnt(0)
	v_mfma_f32_16x16x32_bf16 v[124:127], v[158:161], v[174:177], v[124:127]
	v_mfma_f32_16x16x32_bf16 v[120:123], v[166:169], v[174:177], v[120:123]
	v_mfma_f32_16x16x32_bf16 v[108:111], v[158:161], v[182:185], v[108:111]
	v_mfma_f32_16x16x32_bf16 v[104:107], v[166:169], v[182:185], v[104:107]
	v_mfma_f32_16x16x32_bf16 v[92:95], v[158:161], v[192:195], v[92:95]
	v_mfma_f32_16x16x32_bf16 v[88:91], v[166:169], v[192:195], v[88:91]
	v_mfma_f32_16x16x32_bf16 v[76:79], v[158:161], v[200:203], v[76:79]
	v_mfma_f32_16x16x32_bf16 v[72:75], v[166:169], v[200:203], v[72:75]
	v_mfma_f32_16x16x32_bf16 v[124:127], v[162:165], v[178:181], v[124:127]
	v_mfma_f32_16x16x32_bf16 v[120:123], v[170:173], v[178:181], v[120:123]
	v_mfma_f32_16x16x32_bf16 v[108:111], v[162:165], v[186:189], v[108:111]
	v_mfma_f32_16x16x32_bf16 v[104:107], v[170:173], v[186:189], v[104:107]
	v_mfma_f32_16x16x32_bf16 v[92:95], v[162:165], v[196:199], v[92:95]
	v_mfma_f32_16x16x32_bf16 v[88:91], v[170:173], v[196:199], v[88:91]
	v_mfma_f32_16x16x32_bf16 v[76:79], v[162:165], v[204:207], v[76:79]
	v_mfma_f32_16x16x32_bf16 v[72:75], v[170:173], v[204:207], v[72:75]
	s_setprio 0
	s_barrier
	s_add_i32 s30, s58, s42
	v_lshl_add_u64 v[148:149], s[24:25], 0, v[130:131]
	s_mov_b32 m0, s30
	ds_read_b128 v[208:211], v153
	ds_read_b128 v[214:217], v153 offset:1024
	ds_read_b128 v[218:221], v153 offset:2048
	ds_read_b128 v[222:225], v153 offset:3072
	global_load_lds_dwordx4 v[148:149], off
	v_lshl_add_u64 v[226:227], s[24:25], 0, v[134:135]
	s_add_i32 m0, s30, 0x2000
	s_nop 0
	global_load_lds_dwordx4 v[226:227], off
	s_barrier
	s_waitcnt lgkmcnt(0)
	s_setprio 1
	s_waitcnt lgkmcnt(0)
	v_mfma_f32_16x16x32_bf16 v[116:119], v[208:211], v[174:177], v[116:119]
	v_mfma_f32_16x16x32_bf16 v[112:115], v[218:221], v[174:177], v[112:115]
	v_mfma_f32_16x16x32_bf16 v[100:103], v[208:211], v[182:185], v[100:103]
	v_mfma_f32_16x16x32_bf16 v[96:99], v[218:221], v[182:185], v[96:99]
	v_mfma_f32_16x16x32_bf16 v[84:87], v[208:211], v[192:195], v[84:87]
	v_mfma_f32_16x16x32_bf16 v[80:83], v[218:221], v[192:195], v[80:83]
	v_mfma_f32_16x16x32_bf16 v[68:71], v[208:211], v[200:203], v[68:71]
	v_mfma_f32_16x16x32_bf16 v[64:67], v[218:221], v[200:203], v[64:67]
	v_mfma_f32_16x16x32_bf16 v[116:119], v[214:217], v[178:181], v[116:119]
	v_mfma_f32_16x16x32_bf16 v[112:115], v[222:225], v[178:181], v[112:115]
	v_mfma_f32_16x16x32_bf16 v[100:103], v[214:217], v[186:189], v[100:103]
	v_mfma_f32_16x16x32_bf16 v[96:99], v[222:225], v[186:189], v[96:99]
	v_mfma_f32_16x16x32_bf16 v[84:87], v[214:217], v[196:199], v[84:87]
	v_mfma_f32_16x16x32_bf16 v[80:83], v[222:225], v[196:199], v[80:83]
	v_mfma_f32_16x16x32_bf16 v[68:71], v[214:217], v[204:207], v[68:71]
	v_mfma_f32_16x16x32_bf16 v[64:67], v[222:225], v[204:207], v[64:67]
	s_setprio 0
	s_mov_b32 m0, s43
	v_lshl_add_u64 v[228:229], s[26:27], 0, v[128:129]
	s_barrier
	ds_read_b128 v[174:177], v152 offset:16384
	ds_read_b128 v[178:181], v152 offset:17408
	ds_read_b128 v[182:185], v152 offset:18432
	ds_read_b128 v[186:189], v152 offset:19456
	ds_read_b128 v[192:195], v152 offset:20480
	ds_read_b128 v[196:199], v152 offset:21504
	ds_read_b128 v[200:203], v152 offset:22528
	ds_read_b128 v[204:207], v152 offset:23552
	global_load_lds_dwordx4 v[228:229], off
	v_lshl_add_u64 v[230:231], s[26:27], 0, v[132:133]
	s_mov_b32 m0, s44
	s_nop 0
	global_load_lds_dwordx4 v[230:231], off
	s_barrier
	s_waitcnt lgkmcnt(0)
	s_setprio 1
	s_waitcnt lgkmcnt(0)
	v_mfma_f32_16x16x32_bf16 v[60:63], v[158:161], v[174:177], v[60:63]
	v_mfma_f32_16x16x32_bf16 v[56:59], v[166:169], v[174:177], v[56:59]
	v_mfma_f32_16x16x32_bf16 v[44:47], v[158:161], v[182:185], v[44:47]
	v_mfma_f32_16x16x32_bf16 v[40:43], v[166:169], v[182:185], v[40:43]
	v_mfma_f32_16x16x32_bf16 v[28:31], v[158:161], v[192:195], v[28:31]
	v_mfma_f32_16x16x32_bf16 v[24:27], v[166:169], v[192:195], v[24:27]
	v_mfma_f32_16x16x32_bf16 v[12:15], v[158:161], v[200:203], v[12:15]
	v_mfma_f32_16x16x32_bf16 v[8:11], v[166:169], v[200:203], v[8:11]
	v_mfma_f32_16x16x32_bf16 v[60:63], v[162:165], v[178:181], v[60:63]
	v_mfma_f32_16x16x32_bf16 v[56:59], v[170:173], v[178:181], v[56:59]
	v_mfma_f32_16x16x32_bf16 v[44:47], v[162:165], v[186:189], v[44:47]
	v_mfma_f32_16x16x32_bf16 v[40:43], v[170:173], v[186:189], v[40:43]
	v_mfma_f32_16x16x32_bf16 v[28:31], v[162:165], v[196:199], v[28:31]
	v_mfma_f32_16x16x32_bf16 v[24:27], v[170:173], v[196:199], v[24:27]
	v_mfma_f32_16x16x32_bf16 v[12:15], v[162:165], v[204:207], v[12:15]
	v_mfma_f32_16x16x32_bf16 v[8:11], v[170:173], v[204:207], v[8:11]
	s_setprio 0
	s_barrier
; #define PG8_STAGE(bufoff, gbase, voff) do { _Pragma("unroll") for (int _i = 0; _i < 2; ++_i) \
;         __builtin_amdgcn_global_load_lds((const unsigned*)((const char*)(gbase) + (voff)[_i]), (LAS unsigned*)(lds + (bufoff) + ldsw + _i * 8192), 16, 0, 0); } while (0)
; #define PG8_LDA(dst, b, h) do { _Pragma("unroll") for (int m = 0; m < 4; ++m) _Pragma("unroll") for (int k = 0; k < 2; ++k) dst[m][k] = *(const LAS bf16x8*)(lds + PG8_SA(b, h) + aoff + m * 2048 + k * 1024); } while (0)
; #define PG8_LDB(dst, b, h) do { _Pragma("unroll") for (int n = 0; n < 2; ++n) _Pragma("unroll") for (int k = 0; k < 2; ++k) dst[n][k] = *(const LAS bf16x8*)(lds + PG8_SB(b, h) + boff + n * 2048 + k * 1024); } while (0)
; #define PG8_MMA(ai, bj, At, Bt) do { __builtin_amdgcn_s_setprio(1); _Pragma("unroll") for (int m = 0; m < 4; ++m) _Pragma("unroll") for (int n = 0; n < 2; ++n) _Pragma("unroll") for (int k = 0; k < 2; ++k) \
;         acc[ai][bj][m][n] = __builtin_amdgcn_mfma_f32_16x16x32_bf16(Bt[n][k], At[m][k], acc[ai][bj][m][n], 0, 0, 0); __builtin_amdgcn_s_setprio(0); } while (0)
; #define PG8_WAIT_V(n) asm volatile("s_waitcnt vmcnt(" #n ")" ::: "memory")
; #define PG8_WAIT_L(n) asm volatile("s_waitcnt lgkmcnt(" #n ")" ::: "memory")
; #define PG8_BAR __builtin_amdgcn_s_barrier()
; #define PG8_SCHED __builtin_amdgcn_sched_barrier(0)
; #define PG8_LDA(dst, b, h) do { _Pragma("unroll") for (int m = 0; m < 4; ++m) _Pragma("unroll") for (int k = 0; k < 2; ++k) dst[m][k] = *(const LAS bf16x8*)(lds + PG8_SA(b, h) + aoff + m * 2048 + k * 1024); } while (0)
; #define PG8_BAR __builtin_amdgcn_s_barrier()
; template <class Epi, bool AFTER = false>
; __device__ __forceinline__ void gemm_phase(LAS unsigned char* lds, const Gemm g, const StaticOrder& S, const Epi& E) {
;     ...
;             PG8_STAGE(PG8_SB(0, 1), b2 + hstep, voffB);
;             PG8_WAIT_V(6); PG8_BAR; PG8_MMA(1, 1, At, B1); PG8_BAR;
;             PG8_LDB(B0, 1, 0); PG8_SCHED; PG8_LDA(At, 1, 0); PG8_STAGE(PG8_SA(0, 1), a2 + hstep, voffA);
;             PG8_WAIT_L(8); PG8_BAR; PG8_WAIT_L(0); PG8_MMA(0, 0, At, B0); PG8_BAR; PG8_SCHED;
;             PG8_LDB(B1, 1, 1); PG8_STAGE(PG8_SB(1, 0), b3, voffB);
;             PG8_BAR; PG8_WAIT_L(0); PG8_MMA(0, 1, At, B1); PG8_BAR;
;             PG8_LDA(At, 1, 1); PG8_STAGE(PG8_SA(1, 0), a3, voffA);
;             PG8_BAR; PG8_WAIT_L(0); PG8_MMA(1, 0, At, B0); PG8_BAR; PG8_SCHED;
	s_add_u32 s30, s24, 0x40000
	s_addc_u32 s31, s25, 0
	s_add_i32 s34, s59, s42
	v_lshl_add_u64 v[158:159], s[30:31], 0, v[130:131]
	s_mov_b32 m0, s34
	s_nop 0
	global_load_lds_dwordx4 v[158:159], off
	v_lshl_add_u64 v[158:159], s[30:31], 0, v[134:135]
	s_add_i32 m0, s34, 0x2000
	s_nop 0
	global_load_lds_dwordx4 v[158:159], off
	s_waitcnt vmcnt(6)
	s_barrier
	s_setprio 1
	v_mfma_f32_16x16x32_bf16 v[52:55], v[208:211], v[174:177], v[52:55]
	v_mfma_f32_16x16x32_bf16 v[48:51], v[218:221], v[174:177], v[48:51]
	v_mfma_f32_16x16x32_bf16 v[36:39], v[208:211], v[182:185], v[36:39]
	v_mfma_f32_16x16x32_bf16 v[32:35], v[218:221], v[182:185], v[32:35]
	v_mfma_f32_16x16x32_bf16 v[20:23], v[208:211], v[192:195], v[20:23]
	v_mfma_f32_16x16x32_bf16 v[16:19], v[218:221], v[192:195], v[16:19]
	v_mfma_f32_16x16x32_bf16 v[4:7], v[208:211], v[200:203], v[4:7]
	v_mfma_f32_16x16x32_bf16 v[0:3], v[218:221], v[200:203], v[0:3]
	v_mfma_f32_16x16x32_bf16 v[52:55], v[214:217], v[178:181], v[52:55]
	v_mfma_f32_16x16x32_bf16 v[48:51], v[222:225], v[178:181], v[48:51]
	v_mfma_f32_16x16x32_bf16 v[36:39], v[214:217], v[186:189], v[36:39]
	v_mfma_f32_16x16x32_bf16 v[32:35], v[222:225], v[186:189], v[32:35]
	v_mfma_f32_16x16x32_bf16 v[20:23], v[214:217], v[196:199], v[20:23]
	v_mfma_f32_16x16x32_bf16 v[16:19], v[222:225], v[196:199], v[16:19]
	v_mfma_f32_16x16x32_bf16 v[4:7], v[214:217], v[204:207], v[4:7]
	v_mfma_f32_16x16x32_bf16 v[0:3], v[222:225], v[204:207], v[0:3]
	s_setprio 0
	s_add_i32 s30, 0, 0x18000
	v_add_u32_e32 v136, s30, v150
	s_barrier
	ds_read_b128 v[158:161], v136
	ds_read_b128 v[162:165], v136 offset:1024
	ds_read_b128 v[166:169], v136 offset:2048
	ds_read_b128 v[170:173], v136 offset:3072
	s_add_u32 s26, s26, 0x40000
	s_addc_u32 s27, s27, 0
	s_mov_b32 m0, s45
	v_lshl_add_u64 v[208:209], s[26:27], 0, v[128:129]
	ds_read_b128 v[174:177], v152 offset:32768
	ds_read_b128 v[178:181], v152 offset:33792
	ds_read_b128 v[182:185], v152 offset:34816
	ds_read_b128 v[186:189], v152 offset:35840
	ds_read_b128 v[192:195], v152 offset:36864
	ds_read_b128 v[196:199], v152 offset:37888
	ds_read_b128 v[200:203], v152 offset:38912
	ds_read_b128 v[204:207], v152 offset:39936
	global_load_lds_dwordx4 v[208:209], off
	v_lshl_add_u64 v[208:209], s[26:27], 0, v[132:133]
	s_mov_b32 m0, s46
	s_nop 0
	global_load_lds_dwordx4 v[208:209], off
	s_waitcnt lgkmcnt(8)
	s_barrier
	s_waitcnt lgkmcnt(0)
	s_setprio 1
	s_waitcnt lgkmcnt(0)
	v_mfma_f32_16x16x32_bf16 v[124:127], v[158:161], v[174:177], v[124:127]
	v_mfma_f32_16x16x32_bf16 v[120:123], v[166:169], v[174:177], v[120:123]
	v_mfma_f32_16x16x32_bf16 v[108:111], v[158:161], v[182:185], v[108:111]
	v_mfma_f32_16x16x32_bf16 v[104:107], v[166:169], v[182:185], v[104:107]
	v_mfma_f32_16x16x32_bf16 v[92:95], v[158:161], v[192:195], v[92:95]
	v_mfma_f32_16x16x32_bf16 v[88:91], v[166:169], v[192:195], v[88:91]
	v_mfma_f32_16x16x32_bf16 v[76:79], v[158:161], v[200:203], v[76:79]
	v_mfma_f32_16x16x32_bf16 v[72:75], v[166:169], v[200:203], v[72:75]
	v_mfma_f32_16x16x32_bf16 v[124:127], v[162:165], v[178:181], v[124:127]
	v_mfma_f32_16x16x32_bf16 v[120:123], v[170:173], v[178:181], v[120:123]
	v_mfma_f32_16x16x32_bf16 v[108:111], v[162:165], v[186:189], v[108:111]
	v_mfma_f32_16x16x32_bf16 v[104:107], v[170:173], v[186:189], v[104:107]
	v_mfma_f32_16x16x32_bf16 v[92:95], v[162:165], v[196:199], v[92:95]
	v_mfma_f32_16x16x32_bf16 v[88:91], v[170:173], v[196:199], v[88:91]
	v_mfma_f32_16x16x32_bf16 v[76:79], v[162:165], v[204:207], v[76:79]
	v_mfma_f32_16x16x32_bf16 v[72:75], v[170:173], v[204:207], v[72:75]
	s_setprio 0
	s_barrier
	s_add_i32 s26, 0, 0x1c000
	s_add_i32 s27, s30, s42
	v_add_u32_e32 v136, s26, v150
	v_lshl_add_u64 v[148:149], v[148:149], 0, s[10:11]
	s_mov_b32 m0, s27
	ds_read_b128 v[208:211], v136
	ds_read_b128 v[214:217], v136 offset:1024
	ds_read_b128 v[218:221], v136 offset:2048
	ds_read_b128 v[222:225], v136 offset:3072
	global_load_lds_dwordx4 v[148:149], off
	v_lshl_add_u64 v[148:149], v[226:227], 0, s[10:11]
	s_add_i32 m0, s27, 0x2000
	s_nop 0
	global_load_lds_dwordx4 v[148:149], off
	s_barrier
; #define PG8_STAGE(bufoff, gbase, voff) do { _Pragma("unroll") for (int _i = 0; _i < 2; ++_i) \
;         __builtin_amdgcn_global_load_lds((const unsigned*)((const char*)(gbase) + (voff)[_i]), (LAS unsigned*)(lds + (bufoff) + ldsw + _i * 8192), 16, 0, 0); } while (0)
; #define PG8_LDA(dst, b, h) do { _Pragma("unroll") for (int m = 0; m < 4; ++m) _Pragma("unroll") for (int k = 0; k < 2; ++k) dst[m][k] = *(const LAS bf16x8*)(lds + PG8_SA(b, h) + aoff + m * 2048 + k * 1024); } while (0)
; #define PG8_MMA(ai, bj, At, Bt) do { __builtin_amdgcn_s_setprio(1); _Pragma("unroll") for (int m = 0; m < 4; ++m) _Pragma("unroll") for (int n = 0; n < 2; ++n) _Pragma("unroll") for (int k = 0; k < 2; ++k) \
;         acc[ai][bj][m][n] = __builtin_amdgcn_mfma_f32_16x16x32_bf16(Bt[n][k], At[m][k], acc[ai][bj][m][n], 0, 0, 0); __builtin_amdgcn_s_setprio(0); } while (0)
; #define PG8_WAIT_V(n) asm volatile("s_waitcnt vmcnt(" #n ")" ::: "memory")
; #define PG8_WAIT_L(n) asm volatile("s_waitcnt lgkmcnt(" #n ")" ::: "memory")
; #define PG8_BAR __builtin_amdgcn_s_barrier()
; #define PG8_SCHED __builtin_amdgcn_sched_barrier(0)
; #define PG8_LDA(dst, b, h) do { _Pragma("unroll") for (int m = 0; m < 4; ++m) _Pragma("unroll") for (int k = 0; k < 2; ++k) dst[m][k] = *(const LAS bf16x8*)(lds + PG8_SA(b, h) + aoff + m * 2048 + k * 1024); } while (0)
; #define PG8_MMA(ai, bj, At, Bt) do { __builtin_amdgcn_s_setprio(1); _Pragma("unroll") for (int m = 0; m < 4; ++m) _Pragma("unroll") for (int n = 0; n < 2; ++n) _Pragma("unroll") for (int k = 0; k < 2; ++k) \
;         acc[ai][bj][m][n] = __builtin_amdgcn_mfma_f32_16x16x32_bf16(Bt[n][k], At[m][k], acc[ai][bj][m][n], 0, 0, 0); __builtin_amdgcn_s_setprio(0); } while (0)
; #define PG8_WAIT_V(n) asm volatile("s_waitcnt vmcnt(" #n ")" ::: "memory")
; #define PG8_BAR __builtin_amdgcn_s_barrier()
; template <class Epi, bool AFTER = false>
; __device__ __forceinline__ void gemm_phase(LAS unsigned char* lds, const Gemm g, const StaticOrder& S, const Epi& E) {
;     ...
;             PG8_LDA(At, 1, 1); PG8_STAGE(PG8_SA(1, 0), a3, voffA);
;             PG8_BAR; PG8_WAIT_L(0); PG8_MMA(1, 0, At, B0); PG8_BAR; PG8_SCHED;
;             PG8_STAGE(PG8_SB(1, 1), b3 + hstep, voffB);
;             PG8_WAIT_V(6); PG8_BAR; PG8_MMA(1, 1, At, B1); PG8_BAR;
;         }
;         if constexpr (!AFTER) E(acc, cur, wr, wc, fr, fq);
;         if (!has_next) break;
	s_waitcnt lgkmcnt(0)
	s_setprio 1
	s_waitcnt lgkmcnt(0)
	v_mfma_f32_16x16x32_bf16 v[116:119], v[208:211], v[174:177], v[116:119]
	v_mfma_f32_16x16x32_bf16 v[112:115], v[218:221], v[174:177], v[112:115]
	v_mfma_f32_16x16x32_bf16 v[100:103], v[208:211], v[182:185], v[100:103]
	v_mfma_f32_16x16x32_bf16 v[96:99], v[218:221], v[182:185], v[96:99]
	v_mfma_f32_16x16x32_bf16 v[84:87], v[208:211], v[192:195], v[84:87]
	v_mfma_f32_16x16x32_bf16 v[80:83], v[218:221], v[192:195], v[80:83]
	v_mfma_f32_16x16x32_bf16 v[68:71], v[208:211], v[200:203], v[68:71]
	v_mfma_f32_16x16x32_bf16 v[64:67], v[218:221], v[200:203], v[64:67]
	v_mfma_f32_16x16x32_bf16 v[116:119], v[214:217], v[178:181], v[116:119]
	v_mfma_f32_16x16x32_bf16 v[112:115], v[222:225], v[178:181], v[112:115]
	v_mfma_f32_16x16x32_bf16 v[100:103], v[214:217], v[186:189], v[100:103]
	v_mfma_f32_16x16x32_bf16 v[96:99], v[222:225], v[186:189], v[96:99]
	v_mfma_f32_16x16x32_bf16 v[84:87], v[214:217], v[196:199], v[84:87]
	v_mfma_f32_16x16x32_bf16 v[80:83], v[222:225], v[196:199], v[80:83]
	v_mfma_f32_16x16x32_bf16 v[68:71], v[214:217], v[204:207], v[68:71]
	v_mfma_f32_16x16x32_bf16 v[64:67], v[222:225], v[204:207], v[64:67]
	s_setprio 0
	s_mov_b32 m0, s54
	v_lshl_add_u64 v[148:149], v[228:229], 0, s[10:11]
	s_barrier
	ds_read_b128 v[174:177], v152 offset:49152
	ds_read_b128 v[178:181], v152 offset:50176
	ds_read_b128 v[182:185], v152 offset:51200
	ds_read_b128 v[186:189], v152 offset:52224
	ds_read_b128 v[192:195], v152 offset:53248
	ds_read_b128 v[196:199], v152 offset:54272
	ds_read_b128 v[200:203], v152 offset:55296
	ds_read_b128 v[204:207], v152 offset:56320
	global_load_lds_dwordx4 v[148:149], off
	v_lshl_add_u64 v[148:149], v[230:231], 0, s[10:11]
	s_mov_b32 m0, s55
	s_nop 0
	global_load_lds_dwordx4 v[148:149], off
	s_barrier
	s_waitcnt lgkmcnt(0)
	s_setprio 1
	s_waitcnt lgkmcnt(0)
	v_mfma_f32_16x16x32_bf16 v[60:63], v[158:161], v[174:177], v[60:63]
	v_mfma_f32_16x16x32_bf16 v[56:59], v[166:169], v[174:177], v[56:59]
	v_mfma_f32_16x16x32_bf16 v[44:47], v[158:161], v[182:185], v[44:47]
	v_mfma_f32_16x16x32_bf16 v[40:43], v[166:169], v[182:185], v[40:43]
	v_mfma_f32_16x16x32_bf16 v[28:31], v[158:161], v[192:195], v[28:31]
	v_mfma_f32_16x16x32_bf16 v[24:27], v[166:169], v[192:195], v[24:27]
	v_mfma_f32_16x16x32_bf16 v[12:15], v[158:161], v[200:203], v[12:15]
	v_mfma_f32_16x16x32_bf16 v[8:11], v[166:169], v[200:203], v[8:11]
	v_mfma_f32_16x16x32_bf16 v[60:63], v[162:165], v[178:181], v[60:63]
	v_mfma_f32_16x16x32_bf16 v[56:59], v[170:173], v[178:181], v[56:59]
	v_mfma_f32_16x16x32_bf16 v[44:47], v[162:165], v[186:189], v[44:47]
	v_mfma_f32_16x16x32_bf16 v[40:43], v[170:173], v[186:189], v[40:43]
	v_mfma_f32_16x16x32_bf16 v[28:31], v[162:165], v[196:199], v[28:31]
	v_mfma_f32_16x16x32_bf16 v[24:27], v[170:173], v[196:199], v[24:27]
	v_mfma_f32_16x16x32_bf16 v[12:15], v[162:165], v[204:207], v[12:15]
	v_mfma_f32_16x16x32_bf16 v[8:11], v[170:173], v[204:207], v[8:11]
	s_setprio 0
	s_barrier
	s_add_u32 s24, s24, 0x40080
	s_addc_u32 s25, s25, 0
	s_add_i32 s26, s26, s42
	v_lshl_add_u64 v[148:149], s[24:25], 0, v[130:131]
	s_mov_b32 m0, s26
	s_nop 0
	global_load_lds_dwordx4 v[148:149], off
	v_lshl_add_u64 v[148:149], s[24:25], 0, v[134:135]
	s_add_i32 m0, s26, 0x2000
	s_nop 0
	global_load_lds_dwordx4 v[148:149], off
	s_waitcnt vmcnt(6)
	s_barrier
	s_setprio 1
	v_mfma_f32_16x16x32_bf16 v[52:55], v[208:211], v[174:177], v[52:55]
	v_mfma_f32_16x16x32_bf16 v[48:51], v[218:221], v[174:177], v[48:51]
	v_mfma_f32_16x16x32_bf16 v[36:39], v[208:211], v[182:185], v[36:39]
	v_mfma_f32_16x16x32_bf16 v[32:35], v[218:221], v[182:185], v[32:35]
	v_mfma_f32_16x16x32_bf16 v[20:23], v[208:211], v[192:195], v[20:23]
	v_mfma_f32_16x16x32_bf16 v[16:19], v[218:221], v[192:195], v[16:19]
	v_mfma_f32_16x16x32_bf16 v[4:7], v[208:211], v[200:203], v[4:7]
	v_mfma_f32_16x16x32_bf16 v[0:3], v[218:221], v[200:203], v[0:3]
	v_mfma_f32_16x16x32_bf16 v[52:55], v[214:217], v[178:181], v[52:55]
	v_mfma_f32_16x16x32_bf16 v[48:51], v[222:225], v[178:181], v[48:51]
	v_mfma_f32_16x16x32_bf16 v[36:39], v[214:217], v[186:189], v[36:39]
	v_mfma_f32_16x16x32_bf16 v[32:35], v[222:225], v[186:189], v[32:35]
	v_mfma_f32_16x16x32_bf16 v[20:23], v[214:217], v[196:199], v[20:23]
	v_mfma_f32_16x16x32_bf16 v[16:19], v[222:225], v[196:199], v[16:19]
	v_mfma_f32_16x16x32_bf16 v[4:7], v[214:217], v[204:207], v[4:7]
	v_mfma_f32_16x16x32_bf16 v[0:3], v[222:225], v[204:207], v[0:3]
	s_setprio 0
	s_add_i32 s29, s29, 2
	s_add_u32 s22, s22, 0x100
	s_addc_u32 s23, s23, 0
	s_add_u32 s17, s17, 0x100
	s_addc_u32 s28, s28, 0
	s_cmp_gt_u32 s29, 13
	s_barrier
	s_cbranch_scc0 .LBB0_420
	s_cmp_eq_u32 s99, 1
	s_cbranch_scc0 .Lw3_done
	s_mov_b32 s99, 0
	v_readfirstlane_b32 s98, v212
	s_nop 3
	s_cmp_lg_u32 s98, 0
	s_cbranch_scc1 .Lw3_bar
	v_readlane_b32 s98, v254, 3
	s_nop 3
	s_lshl_b32 s98, s98, 8
	v_mov_b32_e32 v250, 0xffc3500
	v_mov_b32_e32 v251, 0xffc2400
	v_add_u32_e32 v251, s98, v251
	s_mov_b32 s98, 0
.Lw3_spin:
	global_load_dword v252, v250, s[88:89] sc1
	global_load_dword v253, v251, s[88:89] sc1
	s_waitcnt vmcnt(0)
	v_min_u32_e32 v252, v252, v253
	s_nop 1
	v_readfirstlane_b32 s97, v252
	s_nop 3
	s_cmp_ge_u32 s97, 4
	s_cbranch_scc1 .Lw3_bar
	s_sleep 1
	s_add_i32 s98, s98, 1
	s_cmp_lt_u32 s98, 0x40000
	s_cbranch_scc1 .Lw3_spin
